# ret_out_unit: SB halves and V tile prefetched across segments into staging registers
# speedup vs baseline: 1.1857x; 1.0004x over previous
; __device__ void ret_out_unit(const Params& p, int l, int unit, LAS unsigned char* lds, const int tid_in) {
;     ...
;     load_tile<false>(regA, zb + ZC_Q, ZW, n, 0.f, tid);
;     load_tile<false>(regB, zb + ZC_K, ZW, n, 0.f, tid);
;     __syncthreads();
;     ...
;         const bf16_t* sb = (const bf16_t*)(pws(p) + OFF_SB) + (size_t)slot * 65536;
; #pragma unroll 1
;         for (int half = 0; half < 2; ++half) {
;             __syncthreads();
;             load_tile<false>(regB, sb + (size_t)half * 128 * 256, 256, 128, 0.f, tid);
.LBB0_300:
	s_and_b32 s0, s85, 15
	s_add_i32 s0, s0, 1
	s_cmp_lt_i32 s85, 32
	s_cselect_b32 s28, 0, s0
	s_lshl_b32 s0, s28, 7
	s_addk_i32 s0, 0xff90
	s_cmp_lt_i32 s85, 32
	s_mov_b64 s[44:45], s[72:73]
	s_cselect_b32 s73, 16, 0x80
	s_cselect_b32 s0, 0, s0
	s_sub_i32 s1, s85, 32
	s_lshr_b32 s1, s1, 4
	s_cmp_lt_i32 s85, 32
	s_cselect_b32 s29, s85, s1
	s_cmp_gt_i32 s85, 31
	s_cselect_b64 s[26:27], -1, 0
	s_lshr_b32 s1, s29, 3
	s_mulk_i32 s1, 0x810
	s_add_i32 s72, s1, s0
	s_addk_i32 s72, 0x400
	v_mov_b32_e32 v124, v244
	s_and_b32 s24, s29, 7
	s_mul_i32 s1, s72, 0x7000
	v_readlane_b32 s6, v253, 19
	s_mul_hi_i32 s0, s72, 0x7000
	v_readlane_b32 s7, v253, 20
	s_add_u32 s1, s6, s1
	s_addc_u32 s6, s7, s0
	s_lshl_b32 s0, s24, 9
	s_waitcnt vmcnt(0)
	v_lshlrev_b32_e32 v3, 3, v124
	s_add_u32 s0, s1, s0
	v_and_b32_e32 v0, 0xf8, v3
	s_addc_u32 s1, s6, 0
	v_lshlrev_b32_e32 v0, 1, v0
	v_lshl_add_u64 v[4:5], s[0:1], 0, v[0:1]
	s_mov_b64 s[6:7], 0x1000
	v_ashrrev_i32_e32 v74, 5, v124
	s_mov_b64 s[46:47], s[2:3]
	s_mov_b64 s[2:3], s[4:5]
	s_mov_b64 s[4:5], s[66:67]
	v_readfirstlane_b32 s80, v124
	v_add_u32_e32 v76, 0x10, v74
	v_add_u32_e32 v78, 0x20, v74
	v_add_u32_e32 v80, 0x30, v74
	v_add_u32_e32 v82, 0x40, v74
	v_add_u32_e32 v84, 0x50, v74
	v_add_u32_e32 v86, 0x60, v74
	v_add_u32_e32 v88, 0x70, v74
	v_cmp_gt_i32_e64 s[6:7], s73, v74
	v_cmp_gt_i32_e64 s[8:9], s73, v76
	v_cmp_gt_i32_e64 s[10:11], s73, v78
	v_cmp_gt_i32_e64 s[12:13], s73, v80
	v_cmp_gt_i32_e64 s[14:15], s73, v82
	v_cmp_gt_i32_e64 s[16:17], s73, v84
	v_cmp_gt_i32_e64 s[18:19], s73, v86
	v_cmp_gt_i32_e64 s[20:21], s73, v88
	v_mul_u32_u24_e32 v3, 0x7000, v74
	v_add_u32_e32 v3, v3, v0
	v_and_b32_e32 v4, 3, v74
	v_bfe_u32 v5, v74, 2, 2
	v_lshl_or_b32 v4, v4, 2, v5
	v_and_b32_e32 v5, 15, v124
	v_xor_b32_e32 v4, v4, v5
	v_lshlrev_b32_e32 v4, 4, v4
	v_lshl_add_u32 v4, v74, 8, v4
	v_bfe_u32 v5, v124, 4, 1
	v_lshl_add_u32 v5, v5, 15, v4
	v_add_u32_e32 v125, 0x10000, v5
	v_add_u32_e32 v126, 0x11000, v5
	v_add_u32_e32 v127, 0x12000, v5
	v_add_u32_e32 v128, 0x13000, v5
	v_add_u32_e32 v129, 0x14000, v5
	v_add_u32_e32 v130, 0x15000, v5
	v_add_u32_e32 v131, 0x16000, v5
	v_add_u32_e32 v132, 0x17000, v5
	s_add_u32 s22, s0, 0x1000
	s_addc_u32 s23, s1, 0
	s_add_u32 s30, s0, 0x2000
	s_addc_u32 s31, s1, 0
	s_cmp_eq_u32 s73, 16
	s_cbranch_scc1 .Lro_small
	global_load_dwordx4 v[8:11], v3, s[22:23]
	s_add_u32 s22, s22, 0x70000
	s_addc_u32 s23, s23, 0
	global_load_dwordx4 v[12:15], v3, s[22:23]
	s_add_u32 s22, s22, 0x70000
	s_addc_u32 s23, s23, 0
	global_load_dwordx4 v[16:19], v3, s[22:23]
	s_add_u32 s22, s22, 0x70000
	s_addc_u32 s23, s23, 0
	global_load_dwordx4 v[20:23], v3, s[22:23]
	s_add_u32 s22, s22, 0x70000
	s_addc_u32 s23, s23, 0
	global_load_dwordx4 v[24:27], v3, s[22:23]
	s_add_u32 s22, s22, 0x70000
	s_addc_u32 s23, s23, 0
	global_load_dwordx4 v[28:31], v3, s[22:23]
	s_add_u32 s22, s22, 0x70000
	s_addc_u32 s23, s23, 0
	global_load_dwordx4 v[32:35], v3, s[22:23]
	s_add_u32 s22, s22, 0x70000
	s_addc_u32 s23, s23, 0
	global_load_dwordx4 v[36:39], v3, s[22:23]
	global_load_dwordx4 v[40:43], v3, s[30:31]
	s_add_u32 s30, s30, 0x70000
	s_addc_u32 s31, s31, 0
	global_load_dwordx4 v[44:47], v3, s[30:31]
	s_add_u32 s30, s30, 0x70000
	s_addc_u32 s31, s31, 0
	global_load_dwordx4 v[48:51], v3, s[30:31]
	s_add_u32 s30, s30, 0x70000
	s_addc_u32 s31, s31, 0
	global_load_dwordx4 v[52:55], v3, s[30:31]
	s_add_u32 s30, s30, 0x70000
	s_addc_u32 s31, s31, 0
	global_load_dwordx4 v[56:59], v3, s[30:31]
	s_add_u32 s30, s30, 0x70000
	s_addc_u32 s31, s31, 0
	global_load_dwordx4 v[60:63], v3, s[30:31]
	s_add_u32 s30, s30, 0x70000
	s_addc_u32 s31, s31, 0
	global_load_dwordx4 v[64:67], v3, s[30:31]
	s_add_u32 s30, s30, 0x70000
	s_addc_u32 s31, s31, 0
	global_load_dwordx4 v[68:71], v3, s[30:31]
	s_mul_i32 s22, s29, 17
	s_add_i32 s22, s22, s28
	s_lshr_b32 s23, s22, 15
	s_lshl_b32 s22, s22, 17
	v_readlane_b32 s30, v253, 36
	s_add_u32 s22, s43, s22
	s_addc_u32 s23, s30, s23
	v_lshlrev_b32_e32 v184, 9, v74
	v_add_u32_e32 v184, v184, v0
	v_mov_b32_e32 v185, v3
	global_load_dwordx4 v[152:155], v184, s[22:23]
	s_add_u32 s22, s22, 0x2000
	s_addc_u32 s23, s23, 0
	global_load_dwordx4 v[156:159], v184, s[22:23]
	s_add_u32 s22, s22, 0x2000
	s_addc_u32 s23, s23, 0
	global_load_dwordx4 v[160:163], v184, s[22:23]
	s_add_u32 s22, s22, 0x2000
	s_addc_u32 s23, s23, 0
	global_load_dwordx4 v[164:167], v184, s[22:23]
	s_add_u32 s22, s22, 0x2000
	s_addc_u32 s23, s23, 0
	global_load_dwordx4 v[168:171], v184, s[22:23]
	s_add_u32 s22, s22, 0x2000
	s_addc_u32 s23, s23, 0
	global_load_dwordx4 v[172:175], v184, s[22:23]
	s_add_u32 s22, s22, 0x2000
	s_addc_u32 s23, s23, 0
	global_load_dwordx4 v[176:179], v184, s[22:23]
	s_add_u32 s22, s22, 0x2000
	s_addc_u32 s23, s23, 0
	global_load_dwordx4 v[180:183], v184, s[22:23]
	s_waitcnt vmcnt(23)
	ds_write_b128 v5, v[8:11] offset:0
	s_waitcnt vmcnt(22)
	ds_write_b128 v5, v[12:15] offset:4096
	s_waitcnt vmcnt(21)
	ds_write_b128 v5, v[16:19] offset:8192
	s_waitcnt vmcnt(20)
	ds_write_b128 v5, v[20:23] offset:12288
	s_waitcnt vmcnt(19)
	ds_write_b128 v5, v[24:27] offset:16384
	s_waitcnt vmcnt(18)
	ds_write_b128 v5, v[28:31] offset:20480
	s_waitcnt vmcnt(17)
	ds_write_b128 v5, v[32:35] offset:24576
	s_waitcnt vmcnt(16)
	ds_write_b128 v5, v[36:39] offset:28672
	s_waitcnt vmcnt(15)
	ds_write_b128 v125, v[40:43] offset:0
	s_waitcnt vmcnt(14)
	ds_write_b128 v125, v[44:47] offset:4096
	s_waitcnt vmcnt(13)
	ds_write_b128 v125, v[48:51] offset:8192
	s_waitcnt vmcnt(12)
	ds_write_b128 v125, v[52:55] offset:12288
	s_waitcnt vmcnt(11)
	ds_write_b128 v125, v[56:59] offset:16384
	s_waitcnt vmcnt(10)
	ds_write_b128 v125, v[60:63] offset:20480
	s_waitcnt vmcnt(9)
	ds_write_b128 v125, v[64:67] offset:24576
	s_waitcnt vmcnt(8)
	ds_write_b128 v125, v[68:71] offset:28672
	s_branch .Lro_join

; __device__ __forceinline__ unsigned pk_bf16(float lo, float hi) { unsigned r; asm volatile("v_cvt_pk_bf16_f32 %0, %1, %2" : "=v"(r) : "v"(lo), "v"(hi)); return r; }
; __device__ void ret_out_unit(const Params& p, int l, int unit, LAS unsigned char* lds, const int tid_in) {
;     ...
; #pragma unroll 1
;         for (int ks = 0; ks < 8; ++ks) {
;             bf16x8 a[2], bq[4];
; #pragma unroll
;             for (int i = 0; i < 2; ++i) a[i] = frag_direct(regB, jb + i * 16, ks * 32, lane);
; #pragma unroll
;             for (int j = 0; j < 4; ++j) bq[j] = frag_direct(regA, ib + j * 16, ks * 32, lane);
; #pragma unroll
;             for (int i = 0; i < 2; ++i)
; #pragma unroll
;                 for (int j = 0; j < 4; ++j) sc[i][j] = __builtin_amdgcn_mfma_f32_16x16x32_bf16(a[i], bq[j], sc[i][j], 0, 0, 0);
;         }
; #pragma unroll
;         for (int i = 0; i < 2; ++i)
; #pragma unroll
;             for (int j = 0; j < 4; ++j) {
;                 const int ii = ib + j * 16 + lc; float v[4];
; #pragma unroll
;                 for (int jj = 0; jj < 4; ++jj) { const int jx = jb + i * 16 + 4 * g + jj; v[jj] = jx <= ii ? sc[i][j][jj] * exp2f(lg * (float)(ii - jx)) : 0.f; }
;                 pk[i][j].x = pk_bf16(v[0], v[1]); pk[i][j].y = pk_bf16(v[2], v[3]);
;             }
.LBB0_333:
	s_and_b32 s23, s22, 0x80
	v_bitop3_b32 v39, v38, v36, 15 bitop3:0x6c
	v_or_b32_e32 v40, s23, v37
	v_lshlrev_b32_e32 v39, 4, v39
	v_add_lshl_u32 v41, s23, v34, 8
	v_lshlrev_b32_e32 v40, 8, v40
	v_add3_u32 v56, 0, v39, v41
	v_add3_u32 v39, s64, v39, v40
	ds_read_b128 v[40:43], v56
	ds_read_b128 v[44:47], v39
	ds_read_b128 v[48:51], v56 offset:4096
	ds_read_b128 v[52:55], v56 offset:8192
	ds_read_b128 v[56:59], v56 offset:12288
	s_waitcnt lgkmcnt(3)
	v_mfma_f32_16x16x32_bf16 v[30:33], v[44:47], v[40:43], v[30:33]
	s_add_i32 s22, s22, 32
	s_cmpk_eq_i32 s22, 0x100
	v_add_u32_e32 v38, 4, v38
	s_waitcnt lgkmcnt(2)
	v_mfma_f32_16x16x32_bf16 v[26:29], v[44:47], v[48:51], v[26:29]
	s_waitcnt lgkmcnt(1)
	v_mfma_f32_16x16x32_bf16 v[22:25], v[44:47], v[52:55], v[22:25]
	s_waitcnt lgkmcnt(0)
	v_mfma_f32_16x16x32_bf16 v[18:21], v[44:47], v[56:59], v[18:21]
	ds_read_b128 v[44:47], v39 offset:4096
	s_waitcnt lgkmcnt(0)
	v_mfma_f32_16x16x32_bf16 v[14:17], v[44:47], v[40:43], v[14:17]
	v_mfma_f32_16x16x32_bf16 v[6:9], v[44:47], v[48:51], v[6:9]
	v_mfma_f32_16x16x32_bf16 v[10:13], v[44:47], v[52:55], v[10:13]
	v_mfma_f32_16x16x32_bf16 v[2:5], v[44:47], v[56:59], v[2:5]
	s_cbranch_scc0 .LBB0_333
	v_cvt_f32_ubyte0_e32 v36, s24
	v_sub_f32_e32 v36, 0xc0a00000, v36
	v_cmp_gt_f32_e32 vcc, s75, v36
	s_and_b64 s[22:23], vcc, exec
	s_cselect_b32 s22, 0xffffffc0, 0
	v_cndmask_b32_e32 v37, 0, v237, vcc
	v_add_f32_e32 v36, v36, v37
	v_exp_f32_e32 v36, v36
	v_and_or_b32 v35, v35, 12, s61
	s_andn2_b32 s65, s65, 31
	v_ldexp_f32 v38, v36, s22
	v_sub_f32_e32 v39, 1.0, v38
	v_add_f32_e32 v36, -1.0, v39
	v_sub_f32_e32 v37, v36, v39
	v_add_f32_e32 v37, 1.0, v37
	v_sub_f32_e64 v36, -v38, v36
	v_add_f32_e32 v40, v36, v37
	v_frexp_mant_f32_e32 v41, v39
	v_cvt_f64_f32_e32 v[36:37], v39
	s_mov_b32 s22, 0x3f2aaaab
	v_frexp_exp_i32_f64_e32 v36, v[36:37]
	v_cmp_gt_f32_e32 vcc, s22, v41
	s_mov_b32 s22, 0x3f317218
	s_nop 0
	v_subbrev_co_u32_e32 v36, vcc, 0, v36, vcc
	v_sub_u32_e32 v37, 0, v36
	v_ldexp_f32 v39, v39, v37
	v_ldexp_f32 v37, v40, v37
	v_add_f32_e32 v40, -1.0, v39
	v_add_f32_e32 v43, 1.0, v39
	v_add_f32_e32 v41, 1.0, v40
	v_add_f32_e32 v44, -1.0, v43
	v_sub_f32_e32 v41, v39, v41
	v_sub_f32_e32 v39, v39, v44
	v_add_f32_e32 v41, v37, v41
	v_add_f32_e32 v37, v37, v39
	v_add_f32_e32 v39, v43, v37
	v_rcp_f32_e32 v44, v39
	v_add_f32_e32 v42, v40, v41
	v_sub_f32_e32 v40, v42, v40
	v_sub_f32_e32 v40, v41, v40
	v_sub_f32_e32 v41, v39, v43
	v_sub_f32_e32 v37, v37, v41
	v_mul_f32_e32 v41, v42, v44
	v_mul_f32_e32 v43, v39, v41
	v_fma_f32 v45, v41, v39, -v43
	v_fmac_f32_e32 v45, v41, v37
	v_add_f32_e32 v46, v43, v45
	v_sub_f32_e32 v47, v42, v46
	v_sub_f32_e32 v42, v42, v47
	v_sub_f32_e32 v43, v46, v43
	v_sub_f32_e32 v42, v42, v46
	v_add_f32_e32 v40, v40, v42
	v_sub_f32_e32 v42, v43, v45
	v_add_f32_e32 v40, v42, v40
	v_add_f32_e32 v42, v47, v40
	v_mul_f32_e32 v43, v44, v42
	v_mul_f32_e32 v45, v39, v43
	v_fma_f32 v39, v43, v39, -v45
	v_fmac_f32_e32 v39, v43, v37
	v_sub_f32_e32 v37, v47, v42
	v_add_f32_e32 v37, v40, v37
	v_add_f32_e32 v40, v45, v39
	v_sub_f32_e32 v46, v42, v40
	v_sub_f32_e32 v42, v42, v46
	v_sub_f32_e32 v45, v40, v45
	v_sub_f32_e32 v40, v42, v40
	v_add_f32_e32 v37, v37, v40
	v_sub_f32_e32 v39, v45, v39
	v_cvt_f32_i32_e32 v36, v36
	v_add_f32_e32 v37, v39, v37
	v_add_f32_e32 v39, v41, v43
	v_add_f32_e32 v37, v46, v37
	v_sub_f32_e32 v40, v39, v41
	v_mul_f32_e32 v37, v44, v37
	v_sub_f32_e32 v40, v43, v40
	v_add_f32_e32 v37, v40, v37
	v_mul_f32_e32 v43, 0x3f317218, v36
	v_add_f32_e32 v40, v39, v37
	v_fma_f32 v44, v36, s22, -v43
	v_mul_f32_e32 v41, v40, v40
	v_fmac_f32_e32 v44, 0xb102e308, v36
	v_sub_f32_e32 v36, v40, v39
	v_fmamk_f32 v42, v41, 0x3e9b6dac, v234
	v_sub_f32_e32 v36, v37, v36
	v_add_f32_e32 v37, v43, v44
	v_fmaak_f32 v42, v41, v42, 0x3f2aaada
	v_sub_f32_e32 v39, v37, v43
	v_ldexp_f32 v43, v40, 1
	v_mul_f32_e32 v40, v40, v41
	v_mul_f32_e32 v40, v40, v42
	v_add_f32_e32 v41, v43, v40
	v_sub_f32_e32 v42, v41, v43
	v_ldexp_f32 v36, v36, 1
	v_sub_f32_e32 v40, v40, v42
	v_add_f32_e32 v36, v36, v40
	v_add_f32_e32 v40, v41, v36
	v_sub_f32_e32 v41, v40, v41
	v_sub_f32_e32 v36, v36, v41
	v_add_f32_e32 v41, v37, v40
	v_sub_f32_e32 v42, v41, v37
	v_sub_f32_e32 v43, v41, v42
	v_sub_f32_e32 v39, v44, v39
	v_sub_f32_e32 v37, v37, v43
	v_sub_f32_e32 v40, v40, v42
	v_add_f32_e32 v37, v40, v37
	v_add_f32_e32 v40, v39, v36
	v_sub_f32_e32 v42, v40, v39
	v_sub_f32_e32 v43, v40, v42
	v_sub_f32_e32 v39, v39, v43
	v_sub_f32_e32 v36, v36, v42
	v_add_f32_e32 v37, v40, v37
	v_add_f32_e32 v36, v36, v39
	v_add_f32_e32 v39, v41, v37
	v_sub_f32_e32 v40, v39, v41
	v_sub_f32_e32 v37, v37, v40
	v_add_f32_e32 v36, v36, v37
	v_add_f32_e32 v36, v39, v36
	v_cmp_nlt_f32_e32 vcc, 1.0, v38
	v_sub_u32_e32 v37, v34, v35
	v_cvt_f32_i32_e32 v37, v37
	v_cndmask_b32_e32 v36, v238, v36, vcc
	v_cmp_neq_f32_e32 vcc, 1.0, v38
	s_mov_b32 s22, 0x33800000
	s_nop 0
	v_cndmask_b32_e32 v36, v239, v36, vcc
	v_cmp_gt_f32_e32 vcc, s22, v38
	s_nop 1
	v_cndmask_b32_e64 v36, v36, -v38, vcc
	v_mul_f32_e32 v133, 0x3fb8aa3b, v36
	v_mul_f32_e32 v36, v133, v37
	v_cmp_gt_f32_e32 vcc, s75, v36
	s_nop 1
	v_cndmask_b32_e32 v36, 0, v237, vcc
	v_fmac_f32_e32 v36, v133, v37
	v_or_b32_e32 v37, 1, v35
	v_sub_u32_e32 v38, v34, v37
	v_exp_f32_e32 v36, v36
	v_cvt_f32_i32_e32 v38, v38
	v_cndmask_b32_e32 v39, 0, v240, vcc
	v_cmp_lt_i32_e32 vcc, v34, v35
	v_ldexp_f32 v36, v36, v39
	v_mul_f32_e32 v39, v133, v38
	v_cmp_gt_f32_e64 s[22:23], s75, v39
	v_mul_f32_e32 v30, v36, v30
	v_cndmask_b32_e64 v30, v30, 0, vcc
	v_cndmask_b32_e64 v39, 0, v237, s[22:23]
	v_fmac_f32_e32 v39, v133, v38
	v_exp_f32_e32 v38, v39
	v_cndmask_b32_e64 v39, 0, v240, s[22:23]
; __device__ __forceinline__ unsigned pk_bf16(float lo, float hi) { unsigned r; asm volatile("v_cvt_pk_bf16_f32 %0, %1, %2" : "=v"(r) : "v"(lo), "v"(hi)); return r; }
; __device__ void ret_out_unit(const Params& p, int l, int unit, LAS unsigned char* lds, const int tid_in) {
;     ...
; #pragma unroll
;         for (int i = 0; i < 2; ++i)
; #pragma unroll
;             for (int j = 0; j < 4; ++j) {
;                 const int ii = ib + j * 16 + lc; float v[4];
; #pragma unroll
;                 for (int jj = 0; jj < 4; ++jj) { const int jx = jb + i * 16 + 4 * g + jj; v[jj] = jx <= ii ? sc[i][j][jj] * exp2f(lg * (float)(ii - jx)) : 0.f; }
;                 pk[i][j].x = pk_bf16(v[0], v[1]); pk[i][j].y = pk_bf16(v[2], v[3]);
;             }
	v_cmp_gt_i32_e64 s[22:23], v34, v35
	v_mul_f32_e32 v6, v36, v6
	v_ldexp_f32 v38, v38, v39
	v_or_b32_e32 v39, 2, v35
	v_sub_u32_e32 v40, v34, v39
	v_cvt_f32_i32_e32 v40, v40
	v_mul_f32_e32 v31, v38, v31
	v_cndmask_b32_e64 v31, 0, v31, s[22:23]
	v_cvt_pk_bf16_f32 v90, v30, v31
	v_mul_f32_e32 v38, v133, v40
	v_cmp_gt_f32_e64 s[22:23], s75, v38
	v_cmp_ge_i32_e64 s[24:25], v34, v39
	v_cndmask_b32_e64 v6, v6, 0, vcc
	v_cndmask_b32_e64 v38, 0, v237, s[22:23]
	v_fmac_f32_e32 v38, v133, v40
	v_or_b32_e32 v40, 3, v35
	v_exp_f32_e32 v38, v38
	v_sub_u32_e32 v41, v34, v40
	v_cvt_f32_i32_e32 v41, v41
	v_cndmask_b32_e64 v42, 0, v240, s[22:23]
	v_ldexp_f32 v38, v38, v42
	v_mul_f32_e32 v32, v38, v32
	v_mul_f32_e32 v38, v133, v41
	v_cmp_gt_f32_e64 s[22:23], s75, v38
	v_cndmask_b32_e64 v32, 0, v32, s[24:25]
	s_nop 0
	v_cndmask_b32_e64 v38, 0, v237, s[22:23]
	v_fmac_f32_e32 v38, v133, v41
	v_exp_f32_e32 v38, v38
	v_cndmask_b32_e64 v41, 0, v240, s[22:23]
	v_cmp_ge_i32_e64 s[22:23], v34, v40
	v_ldexp_f32 v38, v38, v41
	v_mul_f32_e32 v33, v38, v33
	v_or_b32_e32 v38, 16, v34
	v_sub_u32_e32 v41, v38, v35
	v_cvt_f32_i32_e32 v41, v41
	v_cndmask_b32_e64 v33, 0, v33, s[22:23]
	v_sub_u32_e32 v31, v38, v37
	v_cvt_f32_i32_e32 v31, v31
	v_mul_f32_e32 v30, v133, v41
	v_cmp_gt_f32_e64 s[22:23], s75, v30
	v_cvt_pk_bf16_f32 v91, v32, v33
	v_cmp_ge_i32_e64 s[24:25], v38, v35
	s_nop 0
	v_cndmask_b32_e64 v30, 0, v237, s[22:23]
	v_fmac_f32_e32 v30, v133, v41
	v_exp_f32_e32 v30, v30
	v_cndmask_b32_e64 v32, 0, v240, s[22:23]
	v_ldexp_f32 v30, v30, v32
	v_mul_f32_e32 v26, v30, v26
	v_mul_f32_e32 v30, v133, v31
	v_cmp_gt_f32_e64 s[22:23], s75, v30
	v_cndmask_b32_e64 v26, 0, v26, s[24:25]
	v_cmp_ge_i32_e64 s[24:25], v38, v39
	v_cndmask_b32_e64 v30, 0, v237, s[22:23]
	v_fmac_f32_e32 v30, v133, v31
	v_exp_f32_e32 v30, v30
	v_cndmask_b32_e64 v31, 0, v240, s[22:23]
	v_cmp_gt_i32_e64 s[22:23], v38, v35
	v_ldexp_f32 v30, v30, v31
	v_sub_u32_e32 v31, v38, v39
	v_cvt_f32_i32_e32 v31, v31
	v_mul_f32_e32 v27, v30, v27
	v_cndmask_b32_e64 v27, 0, v27, s[22:23]
	v_cvt_pk_bf16_f32 v92, v26, v27
	v_mul_f32_e32 v30, v133, v31
	v_cmp_gt_f32_e64 s[22:23], s75, v30
	s_nop 1
	v_cndmask_b32_e64 v30, 0, v237, s[22:23]
	v_fmac_f32_e32 v30, v133, v31
	v_exp_f32_e32 v30, v30
	v_sub_u32_e32 v31, v38, v40
	v_cvt_f32_i32_e32 v31, v31
	v_cndmask_b32_e64 v32, 0, v240, s[22:23]
	v_ldexp_f32 v30, v30, v32
	v_mul_f32_e32 v28, v30, v28
	v_mul_f32_e32 v30, v133, v31
	v_cmp_gt_f32_e64 s[22:23], s75, v30
	v_cndmask_b32_e64 v28, 0, v28, s[24:25]
	s_nop 0
	v_cndmask_b32_e64 v30, 0, v237, s[22:23]
	v_fmac_f32_e32 v30, v133, v31
	v_exp_f32_e32 v30, v30
	v_cndmask_b32_e64 v31, 0, v240, s[22:23]
	v_cmp_ge_i32_e64 s[22:23], v38, v40
	v_ldexp_f32 v30, v30, v31
	v_mul_f32_e32 v29, v30, v29
	v_or_b32_e32 v30, 32, v34
	v_sub_u32_e32 v31, v30, v35
	v_cvt_f32_i32_e32 v31, v31
	v_cndmask_b32_e64 v29, 0, v29, s[22:23]
	v_sub_u32_e32 v27, v30, v37
	v_cvt_f32_i32_e32 v27, v27
	v_mul_f32_e32 v26, v133, v31
	v_cmp_gt_f32_e64 s[22:23], s75, v26
	v_cvt_pk_bf16_f32 v93, v28, v29
	v_cmp_ge_i32_e64 s[24:25], v30, v35
	s_nop 0
	v_cndmask_b32_e64 v26, 0, v237, s[22:23]
	v_fmac_f32_e32 v26, v133, v31
	v_exp_f32_e32 v26, v26
	v_cndmask_b32_e64 v28, 0, v240, s[22:23]
	v_ldexp_f32 v26, v26, v28
	v_mul_f32_e32 v22, v26, v22
	v_mul_f32_e32 v26, v133, v27
	v_cmp_gt_f32_e64 s[22:23], s75, v26
	v_cndmask_b32_e64 v22, 0, v22, s[24:25]
	v_cmp_ge_i32_e64 s[24:25], v30, v39
	v_cndmask_b32_e64 v26, 0, v237, s[22:23]
	v_fmac_f32_e32 v26, v133, v27
	v_exp_f32_e32 v26, v26
	v_cndmask_b32_e64 v27, 0, v240, s[22:23]
	v_cmp_gt_i32_e64 s[22:23], v30, v35
	v_ldexp_f32 v26, v26, v27
	v_sub_u32_e32 v27, v30, v39
	v_cvt_f32_i32_e32 v27, v27
	v_mul_f32_e32 v23, v26, v23
	v_cndmask_b32_e64 v23, 0, v23, s[22:23]
	v_cvt_pk_bf16_f32 v94, v22, v23
	v_mul_f32_e32 v26, v133, v27
	v_cmp_gt_f32_e64 s[22:23], s75, v26
	s_nop 1
	v_cndmask_b32_e64 v26, 0, v237, s[22:23]
	v_fmac_f32_e32 v26, v133, v27
	v_exp_f32_e32 v26, v26
	v_sub_u32_e32 v27, v30, v40
	v_cvt_f32_i32_e32 v27, v27
	v_cndmask_b32_e64 v28, 0, v240, s[22:23]
	v_ldexp_f32 v26, v26, v28
	v_mul_f32_e32 v24, v26, v24
	v_mul_f32_e32 v26, v133, v27
	v_cmp_gt_f32_e64 s[22:23], s75, v26
	v_cndmask_b32_e64 v24, 0, v24, s[24:25]
	s_nop 0
	v_cndmask_b32_e64 v26, 0, v237, s[22:23]
	v_fmac_f32_e32 v26, v133, v27
	v_exp_f32_e32 v26, v26
	v_cndmask_b32_e64 v27, 0, v240, s[22:23]
	v_cmp_ge_i32_e64 s[22:23], v30, v40
	v_ldexp_f32 v26, v26, v27
	v_mul_f32_e32 v25, v26, v25
	v_or_b32_e32 v26, 48, v34
	v_sub_u32_e32 v27, v26, v35
	v_cvt_f32_i32_e32 v27, v27
	v_cndmask_b32_e64 v25, 0, v25, s[22:23]
	v_sub_u32_e32 v23, v26, v37
	v_cvt_f32_i32_e32 v23, v23
	v_mul_f32_e32 v22, v133, v27
	v_cmp_gt_f32_e64 s[22:23], s75, v22
	v_cvt_pk_bf16_f32 v95, v24, v25
	v_cmp_ge_i32_e64 s[24:25], v26, v35
	s_nop 0
	v_cndmask_b32_e64 v22, 0, v237, s[22:23]
	v_fmac_f32_e32 v22, v133, v27
	v_exp_f32_e32 v22, v22
	v_cndmask_b32_e64 v24, 0, v240, s[22:23]
	v_ldexp_f32 v22, v22, v24
	v_mul_f32_e32 v18, v22, v18
	v_mul_f32_e32 v22, v133, v23
	v_cmp_gt_f32_e64 s[22:23], s75, v22
	v_cndmask_b32_e64 v18, 0, v18, s[24:25]
	v_cmp_ge_i32_e64 s[24:25], v26, v39
	v_cndmask_b32_e64 v22, 0, v237, s[22:23]
	v_fmac_f32_e32 v22, v133, v23
	v_exp_f32_e32 v22, v22
	v_cndmask_b32_e64 v23, 0, v240, s[22:23]
	v_cmp_gt_i32_e64 s[22:23], v26, v35
	v_ldexp_f32 v22, v22, v23
	v_sub_u32_e32 v23, v26, v39
	v_cvt_f32_i32_e32 v23, v23
	v_mul_f32_e32 v19, v22, v19
	v_cndmask_b32_e64 v19, 0, v19, s[22:23]
	v_cvt_pk_bf16_f32 v96, v18, v19
	v_mul_f32_e32 v22, v133, v23
	v_cmp_gt_f32_e64 s[22:23], s75, v22
	v_or_b32_e32 v19, 17, v35
	v_cmp_ge_i32_e32 vcc, v38, v19
	v_cndmask_b32_e64 v22, 0, v237, s[22:23]
; __device__ __forceinline__ unsigned pk_bf16(float lo, float hi) { unsigned r; asm volatile("v_cvt_pk_bf16_f32 %0, %1, %2" : "=v"(r) : "v"(lo), "v"(hi)); return r; }
; __device__ void ret_out_unit(const Params& p, int l, int unit, LAS unsigned char* lds, const int tid_in) {
;     ...
; #pragma unroll
;         for (int i = 0; i < 2; ++i)
; #pragma unroll
;             for (int j = 0; j < 4; ++j) {
;                 const int ii = ib + j * 16 + lc; float v[4];
; #pragma unroll
;                 for (int jj = 0; jj < 4; ++jj) { const int jx = jb + i * 16 + 4 * g + jj; v[jj] = jx <= ii ? sc[i][j][jj] * exp2f(lg * (float)(ii - jx)) : 0.f; }
;                 pk[i][j].x = pk_bf16(v[0], v[1]); pk[i][j].y = pk_bf16(v[2], v[3]);
;             }
;     }
;     const int ib2 = (wid >> 1) * 32, eb = (wid & 1) * 128;
;     f32x4 acc[2][8];
; #pragma unroll
;     for (int i = 0; i < 2; ++i)
; #pragma unroll
;         for (int j = 0; j < 8; ++j) acc[i][j] = (f32x4){0.f, 0.f, 0.f, 0.f};
;     if (c > 0) {
	v_fmac_f32_e32 v22, v133, v23
	v_exp_f32_e32 v22, v22
	v_sub_u32_e32 v23, v26, v40
	v_cvt_f32_i32_e32 v23, v23
	v_cndmask_b32_e64 v24, 0, v240, s[22:23]
	v_ldexp_f32 v22, v22, v24
	v_mul_f32_e32 v20, v22, v20
	v_mul_f32_e32 v22, v133, v23
	v_cmp_gt_f32_e64 s[22:23], s75, v22
	v_cndmask_b32_e64 v20, 0, v20, s[24:25]
	s_nop 0
	v_cndmask_b32_e64 v22, 0, v237, s[22:23]
	v_fmac_f32_e32 v22, v133, v23
	v_exp_f32_e32 v22, v22
	v_cndmask_b32_e64 v23, 0, v240, s[22:23]
	v_cmp_ge_i32_e64 s[22:23], v26, v40
	v_ldexp_f32 v22, v22, v23
	v_mul_f32_e32 v21, v22, v21
	v_or_b32_e32 v22, 16, v35
	v_sub_u32_e32 v23, v34, v22
	v_cvt_f32_i32_e32 v23, v23
	v_cndmask_b32_e64 v21, 0, v21, s[22:23]
	v_cvt_pk_bf16_f32 v97, v20, v21
	v_sub_u32_e32 v20, v34, v19
	v_mul_f32_e32 v18, v133, v23
	v_cmp_gt_f32_e64 s[22:23], s75, v18
	v_cvt_f32_i32_e32 v20, v20
	v_cmp_ge_i32_e64 s[24:25], v34, v22
	v_cndmask_b32_e64 v18, 0, v237, s[22:23]
	v_fmac_f32_e32 v18, v133, v23
	v_exp_f32_e32 v18, v18
	v_cndmask_b32_e64 v21, 0, v240, s[22:23]
	v_ldexp_f32 v18, v18, v21
	v_mul_f32_e32 v14, v18, v14
	v_mul_f32_e32 v18, v133, v20
	v_cmp_gt_f32_e64 s[22:23], s75, v18
	v_cndmask_b32_e64 v14, 0, v14, s[24:25]
	s_nop 0
	v_cndmask_b32_e64 v18, 0, v237, s[22:23]
	v_fmac_f32_e32 v18, v133, v20
	v_exp_f32_e32 v18, v18
	v_cndmask_b32_e64 v20, 0, v240, s[22:23]
	v_cmp_ge_i32_e64 s[22:23], v34, v19
	v_ldexp_f32 v18, v18, v20
	v_or_b32_e32 v20, 18, v35
	v_sub_u32_e32 v21, v34, v20
	v_cvt_f32_i32_e32 v21, v21
	v_mul_f32_e32 v15, v18, v15
	v_cndmask_b32_e64 v15, 0, v15, s[22:23]
	v_cvt_pk_bf16_f32 v98, v14, v15
	v_mul_f32_e32 v18, v133, v21
	v_cmp_gt_f32_e64 s[22:23], s75, v18
	v_cmp_ge_i32_e64 s[24:25], v34, v20
	s_nop 0
	v_cndmask_b32_e64 v18, 0, v237, s[22:23]
	v_fmac_f32_e32 v18, v133, v21
	v_or_b32_e32 v21, 19, v35
	v_exp_f32_e32 v18, v18
	v_sub_u32_e32 v23, v34, v21
	v_cvt_f32_i32_e32 v23, v23
	v_cndmask_b32_e64 v24, 0, v240, s[22:23]
	v_ldexp_f32 v18, v18, v24
	v_mul_f32_e32 v16, v18, v16
	v_mul_f32_e32 v18, v133, v23
	v_cmp_gt_f32_e64 s[22:23], s75, v18
	v_cndmask_b32_e64 v16, 0, v16, s[24:25]
	s_nop 0
	v_cndmask_b32_e64 v18, 0, v237, s[22:23]
	v_fmac_f32_e32 v18, v133, v23
	v_exp_f32_e32 v18, v18
	v_cndmask_b32_e64 v23, 0, v240, s[22:23]
	v_cmp_ge_i32_e64 s[22:23], v34, v21
	v_ldexp_f32 v18, v18, v23
	v_mul_f32_e32 v17, v18, v17
	v_sub_u32_e32 v18, v38, v19
	v_cvt_f32_i32_e32 v18, v18
	v_cndmask_b32_e64 v17, 0, v17, s[22:23]
	v_cvt_pk_bf16_f32 v99, v16, v17
	v_mul_f32_e32 v14, v133, v18
	v_cmp_gt_f32_e64 s[22:23], s75, v14
	s_nop 1
	v_cndmask_b32_e64 v14, 0, v237, s[22:23]
	v_fmac_f32_e32 v14, v133, v18
	v_exp_f32_e32 v14, v14
	v_cndmask_b32_e64 v15, 0, v240, s[22:23]
	v_cmp_ge_i32_e64 s[22:23], v38, v20
	v_ldexp_f32 v14, v14, v15
	v_sub_u32_e32 v15, v38, v20
	v_cvt_f32_i32_e32 v15, v15
	v_mul_f32_e32 v7, v14, v7
	v_cndmask_b32_e32 v7, 0, v7, vcc
	v_cvt_pk_bf16_f32 v100, v6, v7
	v_mul_f32_e32 v14, v133, v15
	v_cmp_gt_f32_e32 vcc, s75, v14
	v_sub_u32_e32 v7, v30, v19
	v_cvt_f32_i32_e32 v7, v7
	v_cndmask_b32_e32 v14, 0, v237, vcc
	v_fmac_f32_e32 v14, v133, v15
	v_exp_f32_e32 v14, v14
	v_sub_u32_e32 v15, v38, v21
	v_cvt_f32_i32_e32 v15, v15
	v_cndmask_b32_e32 v16, 0, v240, vcc
	v_ldexp_f32 v14, v14, v16
	v_mul_f32_e32 v8, v14, v8
	v_mul_f32_e32 v14, v133, v15
	v_cmp_gt_f32_e32 vcc, s75, v14
	v_cndmask_b32_e64 v8, 0, v8, s[22:23]
	v_cmp_ge_i32_e64 s[22:23], v30, v22
	v_cndmask_b32_e32 v14, 0, v237, vcc
	v_fmac_f32_e32 v14, v133, v15
	v_exp_f32_e32 v14, v14
	v_cndmask_b32_e32 v15, 0, v240, vcc
	v_cmp_ge_i32_e32 vcc, v38, v21
	v_ldexp_f32 v14, v14, v15
	v_mul_f32_e32 v9, v14, v9
	v_sub_u32_e32 v14, v30, v22
	v_cvt_f32_i32_e32 v14, v14
	v_cndmask_b32_e32 v9, 0, v9, vcc
	v_cvt_pk_bf16_f32 v101, v8, v9
	v_mul_f32_e32 v6, v133, v14
	v_cmp_gt_f32_e32 vcc, s75, v6
	s_nop 1
	v_cndmask_b32_e32 v6, 0, v237, vcc
	v_fmac_f32_e32 v6, v133, v14
	v_exp_f32_e32 v6, v6
	v_cndmask_b32_e32 v8, 0, v240, vcc
	v_ldexp_f32 v6, v6, v8
	v_mul_f32_e32 v8, v133, v7
	v_cmp_gt_f32_e32 vcc, s75, v8
	v_mul_f32_e32 v6, v6, v10
	v_cndmask_b32_e64 v6, 0, v6, s[22:23]
	v_cndmask_b32_e32 v8, 0, v237, vcc
	v_fmac_f32_e32 v8, v133, v7
	v_exp_f32_e32 v7, v8
	v_cndmask_b32_e32 v8, 0, v240, vcc
	v_cmp_ge_i32_e32 vcc, v30, v19
	v_cmp_ge_i32_e64 s[22:23], v30, v20
	v_ldexp_f32 v7, v7, v8
	v_sub_u32_e32 v8, v30, v20
	v_cvt_f32_i32_e32 v8, v8
	v_mul_f32_e32 v7, v7, v11
	v_cndmask_b32_e32 v7, 0, v7, vcc
	v_cvt_pk_bf16_f32 v102, v6, v7
	v_mul_f32_e32 v9, v133, v8
	v_cmp_gt_f32_e32 vcc, s75, v9
	v_sub_u32_e32 v7, v26, v19
	v_cvt_f32_i32_e32 v7, v7
	v_cndmask_b32_e32 v9, 0, v237, vcc
	v_fmac_f32_e32 v9, v133, v8
	v_exp_f32_e32 v8, v9
	v_sub_u32_e32 v9, v30, v21
	v_cvt_f32_i32_e32 v9, v9
	v_cndmask_b32_e32 v10, 0, v240, vcc
	v_ldexp_f32 v8, v8, v10
	v_mul_f32_e32 v8, v8, v12
	v_mul_f32_e32 v10, v133, v9
	v_cmp_gt_f32_e32 vcc, s75, v10
	v_cndmask_b32_e64 v8, 0, v8, s[22:23]
	v_cmp_ge_i32_e64 s[22:23], v26, v22
	v_cndmask_b32_e32 v10, 0, v237, vcc
	v_fmac_f32_e32 v10, v133, v9
	v_exp_f32_e32 v9, v10
	v_cndmask_b32_e32 v10, 0, v240, vcc
	v_cmp_ge_i32_e32 vcc, v30, v21
	v_ldexp_f32 v9, v9, v10
	v_sub_u32_e32 v10, v26, v22
	v_cvt_f32_i32_e32 v10, v10
	v_mul_f32_e32 v9, v9, v13
	v_cndmask_b32_e32 v9, 0, v9, vcc
	v_cvt_pk_bf16_f32 v103, v8, v9
	v_mul_f32_e32 v6, v133, v10
	v_cmp_gt_f32_e32 vcc, s75, v6
	s_nop 1
	v_cndmask_b32_e32 v6, 0, v237, vcc
	v_fmac_f32_e32 v6, v133, v10
	v_exp_f32_e32 v6, v6
	v_cndmask_b32_e32 v8, 0, v240, vcc
	v_ldexp_f32 v6, v6, v8
	v_mul_f32_e32 v2, v6, v2
	v_mul_f32_e32 v6, v133, v7
	v_cmp_gt_f32_e32 vcc, s75, v6
	v_cndmask_b32_e64 v2, 0, v2, s[22:23]
	v_cmp_ge_i32_e64 s[22:23], v26, v20
	v_cndmask_b32_e32 v6, 0, v237, vcc
	v_fmac_f32_e32 v6, v133, v7
	v_exp_f32_e32 v6, v6
	v_cndmask_b32_e32 v7, 0, v240, vcc
	v_cmp_ge_i32_e32 vcc, v26, v19
	v_ldexp_f32 v6, v6, v7
	v_sub_u32_e32 v7, v26, v20
	v_cvt_f32_i32_e32 v7, v7
	v_mul_f32_e32 v3, v6, v3
	v_cndmask_b32_e32 v3, 0, v3, vcc
	v_cvt_pk_bf16_f32 v104, v2, v3
	v_mul_f32_e32 v6, v133, v7
	v_cmp_gt_f32_e32 vcc, s75, v6
	s_nop 1
	v_cndmask_b32_e32 v6, 0, v237, vcc
	v_fmac_f32_e32 v6, v133, v7
	v_exp_f32_e32 v6, v6
	v_sub_u32_e32 v7, v26, v21
	v_cvt_f32_i32_e32 v7, v7
	v_cndmask_b32_e32 v8, 0, v240, vcc
	v_ldexp_f32 v6, v6, v8
	v_mul_f32_e32 v4, v6, v4
	v_mul_f32_e32 v6, v133, v7
	v_cmp_gt_f32_e32 vcc, s75, v6
	v_cndmask_b32_e64 v4, 0, v4, s[22:23]
	s_lshl_b32 s22, s66, 7
	v_cndmask_b32_e32 v6, 0, v237, vcc
	v_fmac_f32_e32 v6, v133, v7
	v_exp_f32_e32 v6, v6
	v_cndmask_b32_e32 v7, 0, v240, vcc
	v_cmp_ge_i32_e32 vcc, v26, v21
	s_and_b32 s60, s22, 0x80
	v_ldexp_f32 v6, v6, v7
	v_mul_f32_e32 v5, v6, v5
	v_cndmask_b32_e32 v5, 0, v5, vcc
	s_and_b64 vcc, exec, s[26:27]
	v_cvt_pk_bf16_f32 v105, v4, v5
	s_cbranch_vccz .LBB0_356
; __device__ __forceinline__ int launder(int v) { asm volatile("" : "+v"(v)); return v; }
; __device__ void ret_out_unit(const Params& p, int l, int unit, LAS unsigned char* lds, const int tid_in) {
;     ...
;     const int ib2 = (wid >> 1) * 32, eb = (wid & 1) * 128;
;     f32x4 acc[2][8];
; #pragma unroll
;     for (int i = 0; i < 2; ++i)
; #pragma unroll
;         for (int j = 0; j < 8; ++j) acc[i][j] = (f32x4){0.f, 0.f, 0.f, 0.f};
;     if (c > 0) {
;         const int lane = launder(tid) & 63, g = lane >> 4;
;         const bf16_t* sb = (const bf16_t*)(pws(p) + OFF_SB) + (size_t)slot * 65536;
; #pragma unroll 1
;         for (int half = 0; half < 2; ++half) {
;             __syncthreads();
;             load_tile<false>(regB, sb + (size_t)half * 128 * 256, 256, 128, 0.f, tid);
;             __syncthreads();
	s_mul_i32 s22, s29, 17
	s_add_i32 s90, s22, s28
	v_mov_b32_e32 v2, v124
	s_lshl_b64 s[22:23], s[90:91], 17
	s_add_u32 s22, s43, s22
	v_readlane_b32 s24, v253, 36
	v_lshlrev_b32_e32 v6, 2, v2
	v_bfe_u32 v7, v2, 2, 2
	v_lshrrev_b32_e32 v8, 3, v2
	s_addc_u32 s23, s24, s23
	v_and_or_b32 v135, v6, 12, v7
	v_lshlrev_b32_e32 v6, 2, v7
	v_and_b32_e32 v8, 2, v8
	v_ashrrev_i32_e32 v77, 31, v76
	s_lshl_b32 s40, s80, 9
	v_lshrrev_b32_e32 v3, 1, v2
	v_and_or_b32 v5, v2, 15, s65
	v_or_b32_e32 v9, v6, v8
	v_ashrrev_i32_e32 v75, 31, v74
	v_lshlrev_b64 v[110:111], 9, v[76:77]
	v_bfe_u32 v11, v2, 1, 1
	s_and_b32 s40, s40, 0x8000
	v_bfe_u32 v77, v2, 4, 2
	v_and_b32_e32 v4, 24, v3
	v_lshlrev_b32_e32 v10, 3, v2
	v_lshlrev_b64 v[108:109], 9, v[74:75]
	v_bitop3_b32 v3, v9, v3, 1 bitop3:0x72
	v_or_b32_e32 v12, 2, v11
	v_or_b32_e32 v14, 4, v11
	v_or_b32_e32 v16, 6, v11
	v_or_b32_e32 v18, 8, v11
	v_or_b32_e32 v20, 10, v11
	v_or_b32_e32 v22, 12, v11
	v_or_b32_e32 v24, 14, v11
	v_lshl_add_u32 v75, v5, 8, 0
	v_lshl_or_b32 v5, v77, 11, s40
	v_and_b32_e32 v10, 8, v10
	v_lshlrev_b32_e32 v3, 4, v3
	v_bitop3_b32 v13, v6, v12, v8 bitop3:0x36
	v_bitop3_b32 v12, v9, v12, 1 bitop3:0x36
	v_bitop3_b32 v15, v6, v14, v8 bitop3:0x36
	v_bitop3_b32 v14, v9, v14, 1 bitop3:0x36
	v_bitop3_b32 v17, v6, v16, v8 bitop3:0x36
	v_bitop3_b32 v16, v9, v16, 1 bitop3:0x36
	v_bitop3_b32 v19, v6, v18, v8 bitop3:0x36
	v_bitop3_b32 v18, v9, v18, 1 bitop3:0x36
	v_bitop3_b32 v21, v6, v20, v8 bitop3:0x36
	v_bitop3_b32 v20, v9, v20, 1 bitop3:0x36
	v_bitop3_b32 v23, v6, v22, v8 bitop3:0x36
	v_bitop3_b32 v22, v9, v22, 1 bitop3:0x36
	v_bitop3_b32 v6, v6, v24, v8 bitop3:0x36
	v_bitop3_b32 v8, v9, v24, 1 bitop3:0x36
	v_lshl_or_b32 v9, v7, 8, v5
	v_readlane_b32 s40, v254, 31
	v_or3_b32 v3, v9, v3, v10
	v_lshlrev_b32_e32 v6, 4, v6
	v_add_u32_e32 v137, s40, v3
	v_add_u32_e32 v3, s60, v4
	v_add_lshl_u32 v3, v3, v7, 8
	v_lshlrev_b32_e32 v23, 4, v23
	v_or3_b32 v4, v3, v6, v10
	v_lshlrev_b32_e32 v21, 4, v21
	v_lshlrev_b32_e32 v8, 4, v8
	v_add_u32_e32 v138, s64, v4
	v_or3_b32 v4, v3, v23, v10
	v_ashrrev_i32_e32 v79, 31, v78
	v_lshlrev_b32_e32 v19, 4, v19
	v_lshlrev_b32_e32 v22, 4, v22
	v_or3_b32 v8, v9, v8, v10
	v_add_u32_e32 v139, s64, v4
	v_or3_b32 v4, v3, v21, v10
	v_lshlrev_b64 v[112:113], 9, v[78:79]
	v_ashrrev_i32_e32 v81, 31, v80
	v_lshlrev_b32_e32 v17, 4, v17
	v_lshlrev_b32_e32 v20, 4, v20
	v_add_u32_e32 v79, s40, v8
	v_or3_b32 v8, v9, v22, v10
	v_add_u32_e32 v140, s64, v4
	v_or3_b32 v4, v3, v19, v10
	v_lshlrev_b64 v[114:115], 9, v[80:81]
	v_ashrrev_i32_e32 v83, 31, v82
	v_lshlrev_b32_e32 v13, 4, v13
	v_lshlrev_b32_e32 v15, 4, v15
	v_lshlrev_b32_e32 v18, 4, v18
	v_add_u32_e32 v81, s40, v8
	v_or3_b32 v8, v9, v20, v10
	v_add_u32_e32 v141, s64, v4
	v_or3_b32 v4, v3, v17, v10
	v_lshrrev_b32_e32 v134, 2, v2
	v_lshlrev_b64 v[116:117], 9, v[82:83]
	v_ashrrev_i32_e32 v85, 31, v84
	v_lshlrev_b32_e32 v16, 4, v16
	v_add_u32_e32 v83, s40, v8
	v_or3_b32 v8, v9, v18, v10
	v_add_u32_e32 v142, s64, v4
	v_or3_b32 v4, v3, v15, v10
	v_or3_b32 v3, v3, v13, v10
	v_lshlrev_b32_e32 v2, 1, v2
	v_lshlrev_b64 v[118:119], 9, v[84:85]
	v_ashrrev_i32_e32 v87, 31, v86
	v_lshlrev_b32_e32 v14, 4, v14
	v_add_u32_e32 v85, s40, v8
	v_or3_b32 v8, v9, v16, v10
	v_add_u32_e32 v144, s64, v3
	v_mul_u32_u24_e32 v3, 0x140, v7
	v_and_b32_e32 v2, 32, v2
	v_lshlrev_b64 v[120:121], 9, v[86:87]
	v_ashrrev_i32_e32 v89, 31, v88
	v_lshlrev_b32_e32 v12, 4, v12
	v_add_u32_e32 v87, s40, v8
	v_or3_b32 v8, v9, v14, v10
	v_or3_b32 v2, v5, v3, v2
	v_lshlrev_b32_e32 v3, 4, v11
	v_lshlrev_b64 v[122:123], 9, v[88:89]
	v_add_u32_e32 v89, s40, v8
	v_or3_b32 v8, v9, v12, v10
	v_or3_b32 v2, v2, v3, v10
	v_mov_b32_e32 v34, v1
	v_mov_b32_e32 v35, v1
	v_mov_b32_e32 v36, v1
	v_mov_b32_e32 v37, v1
	s_movk_i32 s38, 0x80
	v_add_u32_e32 v136, s40, v8
	v_add_u32_e32 v143, s64, v4
	v_add_u32_e32 v145, s64, v2
	v_mov_b64_e32 v[40:41], v[36:37]
	v_mov_b64_e32 v[44:45], v[36:37]
	v_mov_b64_e32 v[52:53], v[36:37]
	v_mov_b64_e32 v[56:57], v[36:37]
	v_mov_b64_e32 v[64:65], v[36:37]
	v_mov_b64_e32 v[60:61], v[36:37]
	v_mov_b64_e32 v[48:49], v[36:37]
	v_mov_b64_e32 v[30:31], v[34:35]
	v_mov_b64_e32 v[26:27], v[34:35]
	v_mov_b64_e32 v[22:23], v[34:35]
	v_mov_b64_e32 v[18:19], v[34:35]
	v_mov_b64_e32 v[14:15], v[34:35]
	v_mov_b64_e32 v[10:11], v[34:35]
	v_mov_b64_e32 v[6:7], v[34:35]
	v_mov_b64_e32 v[2:3], v[34:35]
	v_lshl_add_u64 v[106:107], s[22:23], 0, v[0:1]
	s_mov_b32 s90, 0
	s_mov_b64 s[40:41], -1
	v_mov_b64_e32 v[38:39], v[34:35]
	v_mov_b64_e32 v[42:43], v[34:35]
	v_mov_b64_e32 v[50:51], v[34:35]
	v_mov_b64_e32 v[54:55], v[34:35]
	v_mov_b64_e32 v[62:63], v[34:35]
	v_mov_b64_e32 v[58:59], v[34:35]
	v_mov_b64_e32 v[46:47], v[34:35]
	v_mov_b64_e32 v[32:33], v[36:37]
	v_mov_b64_e32 v[28:29], v[36:37]
	v_mov_b64_e32 v[24:25], v[36:37]
	v_mov_b64_e32 v[20:21], v[36:37]
	v_mov_b64_e32 v[16:17], v[36:37]
	v_mov_b64_e32 v[12:13], v[36:37]
	v_mov_b64_e32 v[8:9], v[36:37]
	v_mov_b64_e32 v[4:5], v[36:37]
; __device__ void ret_out_unit(const Params& p, int l, int unit, LAS unsigned char* lds, const int tid_in) {
;     ...
; #pragma unroll 1
;         for (int half = 0; half < 2; ++half) {
;             __syncthreads();
;             load_tile<false>(regB, sb + (size_t)half * 128 * 256, 256, 128, 0.f, tid);
;             __syncthreads();
.LBB0_336:
	s_barrier
	s_xor_b64 vcc, s[40:41], -1
	v_add_u32_e32 v146, s90, v75
	s_mov_b32 s40, 0
	v_mov_b32_e32 v147, v77
	s_waitcnt vmcnt(7)
	ds_write_b128 v125, v[152:155]
	s_waitcnt vmcnt(6)
	ds_write_b128 v126, v[156:159]
	s_waitcnt vmcnt(5)
	ds_write_b128 v127, v[160:163]
	s_waitcnt vmcnt(4)
	ds_write_b128 v128, v[164:167]
	s_waitcnt vmcnt(3)
	ds_write_b128 v129, v[168:171]
	s_waitcnt vmcnt(2)
	ds_write_b128 v130, v[172:175]
	s_waitcnt vmcnt(1)
	ds_write_b128 v131, v[176:179]
	s_waitcnt vmcnt(0)
	ds_write_b128 v132, v[180:183]
	s_waitcnt lgkmcnt(0)
	s_barrier
	s_cmp_lg_u32 s90, 0
	s_cbranch_scc1 .Lro_pfV
	s_add_u32 s34, s22, 0x10000
	s_addc_u32 s35, s23, 0
	global_load_dwordx4 v[152:155], v184, s[34:35]
	s_add_u32 s34, s34, 0x2000
	s_addc_u32 s35, s35, 0
	global_load_dwordx4 v[156:159], v184, s[34:35]
	s_add_u32 s34, s34, 0x2000
	s_addc_u32 s35, s35, 0
	global_load_dwordx4 v[160:163], v184, s[34:35]
	s_add_u32 s34, s34, 0x2000
	s_addc_u32 s35, s35, 0
	global_load_dwordx4 v[164:167], v184, s[34:35]
	s_add_u32 s34, s34, 0x2000
	s_addc_u32 s35, s35, 0
	global_load_dwordx4 v[168:171], v184, s[34:35]
	s_add_u32 s34, s34, 0x2000
	s_addc_u32 s35, s35, 0
	global_load_dwordx4 v[172:175], v184, s[34:35]
	s_add_u32 s34, s34, 0x2000
	s_addc_u32 s35, s35, 0
	global_load_dwordx4 v[176:179], v184, s[34:35]
	s_add_u32 s34, s34, 0x2000
	s_addc_u32 s35, s35, 0
	global_load_dwordx4 v[180:183], v184, s[34:35]
	s_branch .Lro_pfdone
.Lro_pfV:
	s_add_u32 s34, s0, 0x3000
	s_addc_u32 s35, s1, 0
	global_load_dwordx4 v[152:155], v185, s[34:35]
	s_add_u32 s34, s34, 0x70000
	s_addc_u32 s35, s35, 0
	global_load_dwordx4 v[156:159], v185, s[34:35]
	s_add_u32 s34, s34, 0x70000
	s_addc_u32 s35, s35, 0
	global_load_dwordx4 v[160:163], v185, s[34:35]
	s_add_u32 s34, s34, 0x70000
	s_addc_u32 s35, s35, 0
	global_load_dwordx4 v[164:167], v185, s[34:35]
	s_add_u32 s34, s34, 0x70000
	s_addc_u32 s35, s35, 0
	global_load_dwordx4 v[168:171], v185, s[34:35]
	s_add_u32 s34, s34, 0x70000
	s_addc_u32 s35, s35, 0
	global_load_dwordx4 v[172:175], v185, s[34:35]
	s_add_u32 s34, s34, 0x70000
	s_addc_u32 s35, s35, 0
	global_load_dwordx4 v[176:179], v185, s[34:35]
	s_add_u32 s34, s34, 0x70000
	s_addc_u32 s35, s35, 0
	global_load_dwordx4 v[180:183], v185, s[34:35]
; __device__ void ret_out_unit(const Params& p, int l, int unit, LAS unsigned char* lds, const int tid_in) {
;     ...
; #pragma unroll 1
;             for (int ks = 0; ks < 4; ++ks) {
;                 bf16x8 a[2];
; #pragma unroll
;                 for (int i = 0; i < 2; ++i) a[i] = frag_direct(regA, ib2 + i * 16, half * 128 + ks * 32, lane);
; #pragma unroll
;                 for (int j = 0; j < 8; ++j) { const bf16x8 bs = frag_tr(regB, ks * 32, eb + j * 16, lane);
; #pragma unroll
;                     for (int i = 0; i < 2; ++i) acc[i][j] = __builtin_amdgcn_mfma_f32_16x16x32_bf16(a[i], bs, acc[i][j], 0, 0, 0); }
;             }
;         }
; #pragma unroll
;         for (int i = 0; i < 2; ++i)
; #pragma unroll
;             for (int jj = 0; jj < 4; ++jj) { const float f = exp2f(lg * (float)(ib2 + i * 16 + 4 * g + jj + 1));
; #pragma unroll
;                 for (int j = 0; j < 8; ++j) acc[i][j][jj] *= f; }
.Lro_pfdone:
.LBB0_353:
	v_xor_b32_e32 v66, v147, v135
	v_lshl_add_u32 v70, v66, 4, v146
	v_add_u32_e32 v148, s40, v145
	v_add_u32_e32 v150, s40, v137
	ds_read_b128 v[66:69], v70
	ds_read_b128 v[70:73], v70 offset:4096
	ds_read_b64_tr_b16 v[148:149], v148
	ds_read_b64_tr_b16 v[150:151], v150
	s_waitcnt lgkmcnt(0)
	v_mfma_f32_16x16x32_bf16 v[2:5], v[66:69], v[148:151], v[2:5]
	v_add_u32_e32 v147, 4, v147
	v_mfma_f32_16x16x32_bf16 v[46:49], v[70:73], v[148:151], v[46:49]
	v_add_u32_e32 v148, s40, v144
	v_add_u32_e32 v150, s40, v136
	ds_read_b64_tr_b16 v[148:149], v148
	ds_read_b64_tr_b16 v[150:151], v150
	s_waitcnt lgkmcnt(0)
	v_mfma_f32_16x16x32_bf16 v[6:9], v[66:69], v[148:151], v[6:9]
	v_mfma_f32_16x16x32_bf16 v[58:61], v[70:73], v[148:151], v[58:61]
	v_add_u32_e32 v148, s40, v143
	v_add_u32_e32 v150, s40, v89
	ds_read_b64_tr_b16 v[148:149], v148
	ds_read_b64_tr_b16 v[150:151], v150
	s_waitcnt lgkmcnt(0)
	v_mfma_f32_16x16x32_bf16 v[10:13], v[66:69], v[148:151], v[10:13]
	v_mfma_f32_16x16x32_bf16 v[62:65], v[70:73], v[148:151], v[62:65]
	v_add_u32_e32 v148, s40, v142
	v_add_u32_e32 v150, s40, v87
	ds_read_b64_tr_b16 v[148:149], v148
	ds_read_b64_tr_b16 v[150:151], v150
	s_waitcnt lgkmcnt(0)
	v_mfma_f32_16x16x32_bf16 v[14:17], v[66:69], v[148:151], v[14:17]
	v_mfma_f32_16x16x32_bf16 v[54:57], v[70:73], v[148:151], v[54:57]
	v_add_u32_e32 v148, s40, v141
	v_add_u32_e32 v150, s40, v85
	ds_read_b64_tr_b16 v[148:149], v148
	ds_read_b64_tr_b16 v[150:151], v150
	s_waitcnt lgkmcnt(0)
	v_mfma_f32_16x16x32_bf16 v[18:21], v[66:69], v[148:151], v[18:21]
	v_mfma_f32_16x16x32_bf16 v[50:53], v[70:73], v[148:151], v[50:53]
	v_add_u32_e32 v148, s40, v140
	v_add_u32_e32 v150, s40, v83
	ds_read_b64_tr_b16 v[148:149], v148
	ds_read_b64_tr_b16 v[150:151], v150
	s_waitcnt lgkmcnt(0)
	v_mfma_f32_16x16x32_bf16 v[22:25], v[66:69], v[148:151], v[22:25]
	v_mfma_f32_16x16x32_bf16 v[42:45], v[70:73], v[148:151], v[42:45]
	v_add_u32_e32 v148, s40, v139
	v_add_u32_e32 v150, s40, v81
	ds_read_b64_tr_b16 v[148:149], v148
	ds_read_b64_tr_b16 v[150:151], v150
	s_waitcnt lgkmcnt(0)
	v_mfma_f32_16x16x32_bf16 v[26:29], v[66:69], v[148:151], v[26:29]
	v_mfma_f32_16x16x32_bf16 v[38:41], v[70:73], v[148:151], v[38:41]
	v_add_u32_e32 v148, s40, v138
	v_add_u32_e32 v150, s40, v79
	ds_read_b64_tr_b16 v[148:149], v148
	ds_read_b64_tr_b16 v[150:151], v150
	s_waitcnt lgkmcnt(0)
	v_mfma_f32_16x16x32_bf16 v[30:33], v[66:69], v[148:151], v[30:33]
	s_addk_i32 s40, 0x2000
	s_cmpk_eq_u32 s40, 0x8000
	v_mfma_f32_16x16x32_bf16 v[34:37], v[70:73], v[148:151], v[34:37]
	s_cbranch_scc0 .LBB0_353
	s_mov_b32 s90, 0x8000
	s_mov_b64 s[40:41], 0
	s_and_b64 vcc, exec, vcc
	s_cbranch_vccz .LBB0_336
	v_and_or_b32 v70, v134, 12, s65
	v_or_b32_e32 v66, 1, v70
	v_cvt_f32_i32_e32 v66, v66
	v_mul_f32_e32 v67, v133, v66
	v_cmp_gt_f32_e32 vcc, s75, v67
	s_nop 1
	v_cndmask_b32_e32 v67, 0, v237, vcc
	v_fmac_f32_e32 v67, v133, v66
	v_exp_f32_e32 v66, v67
	v_cndmask_b32_e32 v67, 0, v240, vcc
	v_ldexp_f32 v66, v66, v67
	v_or_b32_e32 v67, 2, v70
	v_cvt_f32_i32_e32 v67, v67
	v_mul_f32_e32 v68, v133, v67
	v_cmp_gt_f32_e32 vcc, s75, v68
	s_nop 1
	v_cndmask_b32_e32 v68, 0, v237, vcc
	v_fmac_f32_e32 v68, v133, v67
	v_exp_f32_e32 v67, v68
	v_cndmask_b32_e32 v68, 0, v240, vcc
	v_ldexp_f32 v67, v67, v68
	v_or_b32_e32 v68, 3, v70
	v_cvt_f32_i32_e32 v68, v68
	v_pk_mul_f32 v[2:3], v[66:67], v[2:3]
	v_pk_mul_f32 v[6:7], v[66:67], v[6:7]
	v_pk_mul_f32 v[10:11], v[66:67], v[10:11]
	v_mul_f32_e32 v69, v133, v68
	v_cmp_gt_f32_e32 vcc, s75, v69
	v_pk_mul_f32 v[14:15], v[66:67], v[14:15]
	v_pk_mul_f32 v[18:19], v[66:67], v[18:19]
	v_cndmask_b32_e32 v69, 0, v237, vcc
	v_fmac_f32_e32 v69, v133, v68
	v_exp_f32_e32 v68, v69
	v_cndmask_b32_e32 v69, 0, v240, vcc
	v_pk_mul_f32 v[22:23], v[66:67], v[22:23]
	v_pk_mul_f32 v[26:27], v[66:67], v[26:27]
	v_ldexp_f32 v68, v68, v69
	v_add_u32_e32 v69, 4, v70
	v_cvt_f32_i32_e32 v69, v69
	v_pk_mul_f32 v[30:31], v[66:67], v[30:31]
	v_or_b32_e32 v66, 17, v70
	v_cvt_f32_i32_e32 v66, v66
	v_mul_f32_e32 v71, v133, v69
	v_cmp_gt_f32_e32 vcc, s75, v71
	v_mul_f32_e32 v67, v133, v66
	s_nop 0
	v_cndmask_b32_e32 v71, 0, v237, vcc
	v_fmac_f32_e32 v71, v133, v69
	v_exp_f32_e32 v69, v71
	v_cndmask_b32_e32 v71, 0, v240, vcc
	v_cmp_gt_f32_e32 vcc, s75, v67
	v_ldexp_f32 v69, v69, v71
	s_nop 0
	v_cndmask_b32_e32 v67, 0, v237, vcc
	v_fmac_f32_e32 v67, v133, v66
	v_exp_f32_e32 v66, v67
	v_cndmask_b32_e32 v67, 0, v240, vcc
	v_pk_mul_f32 v[4:5], v[68:69], v[4:5]
	v_pk_mul_f32 v[8:9], v[68:69], v[8:9]
	v_ldexp_f32 v66, v66, v67
	v_or_b32_e32 v67, 18, v70
	v_cvt_f32_i32_e32 v67, v67
	v_pk_mul_f32 v[12:13], v[68:69], v[12:13]
	v_pk_mul_f32 v[16:17], v[68:69], v[16:17]
	v_pk_mul_f32 v[20:21], v[68:69], v[20:21]
	v_pk_mul_f32 v[24:25], v[68:69], v[24:25]
	v_pk_mul_f32 v[28:29], v[68:69], v[28:29]
	v_pk_mul_f32 v[32:33], v[68:69], v[32:33]
	v_mul_f32_e32 v68, v133, v67
	v_cmp_gt_f32_e32 vcc, s75, v68
	s_nop 1
	v_cndmask_b32_e32 v68, 0, v237, vcc
	v_fmac_f32_e32 v68, v133, v67
	v_exp_f32_e32 v67, v68
	v_cndmask_b32_e32 v68, 0, v240, vcc
	v_ldexp_f32 v67, v67, v68
	v_or_b32_e32 v68, 19, v70
	v_cvt_f32_i32_e32 v68, v68
	v_pk_mul_f32 v[46:47], v[66:67], v[46:47]
	v_pk_mul_f32 v[58:59], v[66:67], v[58:59]
	v_pk_mul_f32 v[62:63], v[66:67], v[62:63]
	v_mul_f32_e32 v69, v133, v68
	v_cmp_gt_f32_e32 vcc, s75, v69
	v_pk_mul_f32 v[54:55], v[66:67], v[54:55]
	v_pk_mul_f32 v[50:51], v[66:67], v[50:51]
	v_cndmask_b32_e32 v69, 0, v237, vcc
	v_fmac_f32_e32 v69, v133, v68
	v_exp_f32_e32 v68, v69
	v_cndmask_b32_e32 v69, 0, v240, vcc
	v_pk_mul_f32 v[42:43], v[66:67], v[42:43]
	v_pk_mul_f32 v[38:39], v[66:67], v[38:39]
	v_ldexp_f32 v68, v68, v69
	v_add_u32_e32 v69, 20, v70
	v_cvt_f32_i32_e32 v69, v69
	v_pk_mul_f32 v[34:35], v[66:67], v[34:35]
	v_mul_f32_e32 v70, v133, v69
	v_cmp_gt_f32_e32 vcc, s75, v70
	s_nop 1
	v_cndmask_b32_e32 v70, 0, v237, vcc
	v_fmac_f32_e32 v70, v133, v69
	v_exp_f32_e32 v69, v70
	v_cndmask_b32_e32 v70, 0, v240, vcc
	v_ldexp_f32 v69, v69, v70
	v_pk_mul_f32 v[48:49], v[68:69], v[48:49]
	v_pk_mul_f32 v[60:61], v[68:69], v[60:61]
	v_pk_mul_f32 v[64:65], v[68:69], v[64:65]
	v_pk_mul_f32 v[56:57], v[68:69], v[56:57]
	v_pk_mul_f32 v[52:53], v[68:69], v[52:53]
	v_pk_mul_f32 v[44:45], v[68:69], v[44:45]
	v_pk_mul_f32 v[40:41], v[68:69], v[40:41]
	v_pk_mul_f32 v[36:37], v[68:69], v[36:37]
	s_branch .LBB0_357

; #define LAS __attribute__((address_space(3)))
; __device__ __forceinline__ int launder(int v) { asm volatile("" : "+v"(v)); return v; }
; __device__ void ret_out_unit(const Params& p, int l, int unit, LAS unsigned char* lds, const int tid_in) {
;     ...
;     __syncthreads();
;     { const int lane = launder(tid) & 63, g = lane >> 4, lc = lane & 15;
; #pragma unroll
;     for (int i = 0; i < 2; ++i)
; #pragma unroll
;         for (int j = 0; j < 4; ++j) *(LAS u32x2*)(regA + img_off(ib + j * 16 + lc, jb + i * 16 + 4 * g)) = pk[i][j]; }
;     load_tile<false>(regB, zb + ZC_V, ZW, n, 0.f, tid);
.LBB0_357:
	v_mov_b32_e32 v66, v124
	s_barrier
	s_mov_b64 s[22:23], 0x3000
	v_lshrrev_b32_e32 v68, 2, v66
	v_lshlrev_b32_e32 v69, 2, v66
	v_and_or_b32 v68, v68, 8, s61
	v_and_b32_e32 v69, 12, v69
	v_bfe_u32 v70, v66, 2, 2
	v_and_or_b32 v67, v66, 15, s62
	v_or_b32_e32 v71, v69, v70
	v_lshrrev_b32_e32 v66, 1, v66
	v_lshrrev_b32_e32 v68, 3, v68
	v_and_b32_e32 v66, 8, v66
	v_bitop3_b32 v69, v68, v69, v70 bitop3:0x1e
	v_bitop3_b32 v68, v68, v71, 2 bitop3:0x36
	v_add_u32_e32 v66, 0, v66
	v_lshlrev_b32_e32 v69, 4, v69
	v_lshlrev_b32_e32 v67, 8, v67
	v_lshlrev_b32_e32 v68, 4, v68
	v_add3_u32 v69, v66, v69, v67
	v_add3_u32 v66, v66, v68, v67
	ds_write2st64_b64 v69, v[90:91], v[92:93] offset1:8
	ds_write2st64_b64 v69, v[94:95], v[96:97] offset0:16 offset1:24
	ds_write2st64_b64 v66, v[98:99], v[100:101] offset1:8
	ds_write2st64_b64 v66, v[102:103], v[104:105] offset0:16 offset1:24
	v_lshl_add_u64 v[66:67], s[0:1], 0, v[0:1]
	v_lshl_add_u64 v[72:73], v[66:67], 0, s[22:23]
	s_cmp_eq_u32 s73, 16
	s_cbranch_scc0 .Lro_vpre
	v_mov_b32_e32 v152, 0
	v_mov_b32_e32 v153, 0
	v_mov_b32_e32 v154, 0
	v_mov_b32_e32 v155, 0
	s_and_saveexec_b64 s[22:23], s[6:7]
	s_cbranch_execz .Lro_vskip0
	v_mad_i64_i32 v[152:153], vcc, v74, s74, v[72:73]
	global_load_dwordx4 v[152:155], v[152:153], off

; __device__ __forceinline__ int launder(int v) { asm volatile("" : "+v"(v)); return v; }
; __device__ void ret_out_unit(const Params& p, int l, int unit, LAS unsigned char* lds, const int tid_in) {
;     ...
;     load_tile<false>(regB, zb + ZC_V, ZW, n, 0.f, tid);
;     __syncthreads();
;     const int ksmax = (ib2 + 31) >> 5;
;     { const int lane = launder(tid) & 63;
; #pragma unroll 1
;     for (int ks = 0; ks <= ksmax; ++ks) {
;         bf16x8 a[2];
; #pragma unroll
;         for (int i = 0; i < 2; ++i) a[i] = frag_direct(regA, ib2 + i * 16, ks * 32, lane);
; #pragma unroll
;         for (int j = 0; j < 8; ++j) { const bf16x8 bs = frag_tr(regB, ks * 32, eb + j * 16, lane);
; #pragma unroll
;             for (int i = 0; i < 2; ++i) acc[i][j] = __builtin_amdgcn_mfma_f32_16x16x32_bf16(a[i], bs, acc[i][j], 0, 0, 0); }
;     } }
.Lro_vskip7:
	s_or_b64 exec, exec, s[22:23]
	s_waitcnt vmcnt(0)
.Lro_vpre:
	s_ashr_i32 s6, s80, 7
	v_mov_b32_e32 v85, v124
	s_waitcnt vmcnt(7)
	ds_write_b128 v125, v[152:155]
	s_waitcnt vmcnt(6)
	ds_write_b128 v126, v[156:159]
	s_waitcnt vmcnt(5)
	ds_write_b128 v127, v[160:163]
	s_waitcnt vmcnt(4)
	ds_write_b128 v128, v[164:167]
	s_waitcnt vmcnt(3)
	ds_write_b128 v129, v[168:171]
	s_waitcnt vmcnt(2)
	ds_write_b128 v130, v[172:175]
	s_waitcnt vmcnt(1)
	ds_write_b128 v131, v[176:179]
	s_waitcnt vmcnt(0)
	ds_write_b128 v132, v[180:183]
	s_cmp_lt_i32 s6, 0
	s_waitcnt lgkmcnt(0)
	s_barrier
	s_cbranch_scc1 .LBB0_376
	v_bfe_u32 v86, v85, 2, 2
	v_lshrrev_b32_e32 v67, 3, v85
	v_lshlrev_b32_e32 v69, 2, v86
	v_and_b32_e32 v70, 2, v67
	v_lshrrev_b32_e32 v68, 1, v85
	v_or_b32_e32 v71, v69, v70
	v_bfe_u32 v87, v85, 1, 1
	v_and_b32_e32 v78, 24, v68
	v_bitop3_b32 v77, v71, v68, 1 bitop3:0x72
	v_or_b32_e32 v68, 2, v87
	v_bitop3_b32 v84, v69, v68, v70 bitop3:0x36
	v_bitop3_b32 v76, v71, v68, 1 bitop3:0x36
	v_or_b32_e32 v68, 4, v87
	v_bitop3_b32 v83, v69, v68, v70 bitop3:0x36
	v_bitop3_b32 v75, v71, v68, 1 bitop3:0x36
	v_or_b32_e32 v68, 6, v87
	v_bitop3_b32 v82, v69, v68, v70 bitop3:0x36
	v_bitop3_b32 v74, v71, v68, 1 bitop3:0x36
	v_or_b32_e32 v68, 8, v87
	v_bitop3_b32 v81, v69, v68, v70 bitop3:0x36
	v_bitop3_b32 v73, v71, v68, 1 bitop3:0x36
	v_or_b32_e32 v68, 10, v87
	s_lshl_b32 s7, s80, 9
	v_bitop3_b32 v80, v69, v68, v70 bitop3:0x36
	v_bitop3_b32 v72, v71, v68, 1 bitop3:0x36
	v_or_b32_e32 v68, 12, v87
	s_and_b32 s7, s7, 0x8000
	v_lshlrev_b32_e32 v66, 2, v85
	v_bitop3_b32 v79, v69, v68, v70 bitop3:0x36
	v_bitop3_b32 v88, v71, v68, 1 bitop3:0x36
	v_or_b32_e32 v68, 14, v87
	v_lshl_or_b32 v90, v86, 8, s7
	v_add_u32_e32 v78, s60, v78
	v_and_or_b32 v0, v85, 15, s65
	v_and_or_b32 v66, v66, 12, v86
	v_lshlrev_b32_e32 v67, 3, v85
	v_bitop3_b32 v89, v69, v68, v70 bitop3:0x36
	v_bitop3_b32 v69, v71, v68, 1 bitop3:0x36
	v_bfe_u32 v68, v85, 4, 2
	v_lshl_or_b32 v71, v88, 4, v90
	v_add_lshl_u32 v88, v78, v86, 8
	v_mul_u32_u24_e32 v86, 0x140, v86
	v_lshlrev_b32_e32 v85, 1, v85
	v_or_b32_e32 v86, s7, v86
	v_and_b32_e32 v85, 32, v85
	v_lshlrev_b32_e32 v87, 4, v87
	v_and_b32_e32 v67, 8, v67
	v_lshl_or_b32 v69, v69, 4, v90
	v_readlane_b32 s8, v254, 31
	v_lshl_or_b32 v72, v72, 4, v90
	v_lshl_or_b32 v73, v73, 4, v90
	v_lshl_or_b32 v74, v74, 4, v90
	v_lshl_or_b32 v75, v75, 4, v90
	v_lshl_or_b32 v76, v76, 4, v90
	v_lshl_or_b32 v77, v77, 4, v90
	v_lshl_or_b32 v78, v89, 4, v88
	v_lshl_or_b32 v79, v79, 4, v88
	v_lshl_or_b32 v80, v80, 4, v88
	v_lshl_or_b32 v81, v81, 4, v88
	v_lshl_or_b32 v82, v82, 4, v88
	v_lshl_or_b32 v83, v83, 4, v88
	v_lshl_or_b32 v84, v84, 4, v88
	v_or3_b32 v85, v86, v85, v87
	s_add_i32 s6, s6, 1
	v_add_u32_e32 v69, s8, v69
	v_lshl_or_b32 v70, v68, 11, v67
	v_add_u32_e32 v71, s8, v71
	v_add_u32_e32 v72, s8, v72
	v_add_u32_e32 v73, s8, v73
	v_add_u32_e32 v74, s8, v74
	v_add_u32_e32 v75, s8, v75
	v_add_u32_e32 v76, s8, v76
	v_add_u32_e32 v77, s8, v77
	v_add_u32_e32 v78, s64, v78
	v_add_u32_e32 v79, s64, v79
	v_add_u32_e32 v80, s64, v80
	v_add_u32_e32 v81, s64, v81
	v_add_u32_e32 v82, s64, v82
	v_add_u32_e32 v83, s64, v83
	v_add_u32_e32 v84, s64, v84
	v_add_u32_e32 v85, s64, v85
	s_mov_b32 s7, 0
